# v89 layout kept byte-for-byte: dead per-XCD generation bump and its wait replaced by same-size s_nops
# speedup vs baseline: 1.0031x; 1.0031x over previous
; __device__ __forceinline__ unsigned xb_add(unsigned* p, unsigned v) { return __hip_atomic_fetch_add(p, v, __ATOMIC_RELAXED, __HIP_MEMORY_SCOPE_AGENT); }
; __device__ __forceinline__ void xcd_barrier(const XcdBarrier& b, const bool leader) {
;     ...
;             xb_add(&bar[XB_XGEN(b.x)], 1u);
;             asm volatile("s_waitcnt vmcnt(0)" ::: "memory");
.LBB0_80:
	s_or_b64 exec, exec, s[8:9]
	s_mov_b64 s[8:9], exec
	v_mbcnt_lo_u32_b32 v2, s8, 0
	v_mbcnt_hi_u32_b32 v2, s9, v2
	v_cmp_eq_u32_e32 vcc, 0, v2
	s_waitcnt vmcnt(0)
	s_and_saveexec_b64 s[10:11], vcc
	s_cbranch_execz .LBB0_82
	s_bcnt1_i32_b64 s1, s[8:9]
	v_mov_b32_e32 v2, 0x2000
	v_mov_b32_e32 v3, s1
	s_nop 0
	s_nop 0
.LBB0_82:
	s_or_b64 exec, exec, s[10:11]
	s_nop 0

; __device__ __forceinline__ unsigned xb_add(unsigned* p, unsigned v) { return __hip_atomic_fetch_add(p, v, __ATOMIC_RELAXED, __HIP_MEMORY_SCOPE_AGENT); }
; __device__ __forceinline__ void xcd_barrier(const XcdBarrier& b, const bool leader) {
;     ...
;             xb_add(&bar[XB_XGEN(b.x)], 1u);
;             asm volatile("s_waitcnt vmcnt(0)" ::: "memory");
.LBB0_341:
	s_or_b64 exec, exec, s[4:5]
	s_mov_b64 s[4:5], exec
	v_mbcnt_lo_u32_b32 v2, s4, 0
	v_mbcnt_hi_u32_b32 v2, s5, v2
	v_cmp_eq_u32_e32 vcc, 0, v2
	s_waitcnt vmcnt(0)
	s_and_saveexec_b64 s[10:11], vcc
	s_cbranch_execz .LBB0_343
	s_bcnt1_i32_b64 s1, s[4:5]
	v_mov_b32_e32 v2, 0x2000
	v_mov_b32_e32 v3, s1
	s_nop 0
	s_nop 0

; __device__ __forceinline__ unsigned xb_add(unsigned* p, unsigned v) { return __hip_atomic_fetch_add(p, v, __ATOMIC_RELAXED, __HIP_MEMORY_SCOPE_AGENT); }
; __device__ __forceinline__ void xcd_barrier(const XcdBarrier& b, const bool leader) {
;     ...
;             xb_add(&bar[XB_XGEN(b.x)], 1u);
;             asm volatile("s_waitcnt vmcnt(0)" ::: "memory");
.LBB0_501:
	s_or_b64 exec, exec, s[6:7]
	s_mov_b64 s[14:15], exec
	v_mbcnt_lo_u32_b32 v2, s14, 0
	v_mbcnt_hi_u32_b32 v2, s15, v2
	v_cmp_eq_u32_e32 vcc, 0, v2
	s_waitcnt vmcnt(0)
	s_and_saveexec_b64 s[6:7], vcc
	s_cbranch_execz .LBB0_503
	s_bcnt1_i32_b64 s2, s[14:15]
	v_mov_b32_e32 v2, s2
	s_nop 0
	s_nop 0
.LBB0_503:
	s_or_b64 exec, exec, s[6:7]
	s_nop 0

; __device__ __forceinline__ unsigned xb_add(unsigned* p, unsigned v) { return __hip_atomic_fetch_add(p, v, __ATOMIC_RELAXED, __HIP_MEMORY_SCOPE_AGENT); }
; __device__ __forceinline__ void xcd_barrier(const XcdBarrier& b, const bool leader) {
;     ...
;             xb_add(&bar[XB_XGEN(b.x)], 1u);
;             asm volatile("s_waitcnt vmcnt(0)" ::: "memory");
.LBB0_613:
	s_or_b64 exec, exec, s[6:7]
	s_mov_b64 s[10:11], exec
	v_mbcnt_lo_u32_b32 v2, s10, 0
	v_mbcnt_hi_u32_b32 v2, s11, v2
	v_cmp_eq_u32_e32 vcc, 0, v2
	s_waitcnt vmcnt(0)
	s_and_saveexec_b64 s[6:7], vcc
	s_cbranch_execz .LBB0_615
	s_bcnt1_i32_b64 s2, s[10:11]
	v_mov_b32_e32 v2, s2
	s_nop 0
	s_nop 0

; __device__ __forceinline__ unsigned xb_add(unsigned* p, unsigned v) { return __hip_atomic_fetch_add(p, v, __ATOMIC_RELAXED, __HIP_MEMORY_SCOPE_AGENT); }
; __device__ __forceinline__ void xcd_barrier(const XcdBarrier& b, const bool leader) {
;     ...
;             xb_add(&bar[XB_XGEN(b.x)], 1u);
;             asm volatile("s_waitcnt vmcnt(0)" ::: "memory");
.LBB0_691:
	s_or_b64 exec, exec, s[4:5]
	s_mov_b64 s[4:5], exec
	v_mbcnt_lo_u32_b32 v2, s4, 0
	v_mbcnt_hi_u32_b32 v2, s5, v2
	v_cmp_eq_u32_e32 vcc, 0, v2
	s_waitcnt vmcnt(0)
	s_and_saveexec_b64 s[6:7], vcc
	s_cbranch_execz .LBB0_693
	s_bcnt1_i32_b64 s2, s[4:5]
	v_mov_b32_e32 v2, s2
	s_nop 0
	s_nop 0

; __device__ __forceinline__ unsigned xb_add(unsigned* p, unsigned v) { return __hip_atomic_fetch_add(p, v, __ATOMIC_RELAXED, __HIP_MEMORY_SCOPE_AGENT); }
; __device__ __forceinline__ void xcd_barrier(const XcdBarrier& b, const bool leader) {
;     ...
;             xb_add(&bar[XB_XGEN(b.x)], 1u);
;             asm volatile("s_waitcnt vmcnt(0)" ::: "memory");
.LBB0_852:
	s_or_b64 exec, exec, s[6:7]
	s_mov_b64 s[12:13], exec
	v_mbcnt_lo_u32_b32 v2, s12, 0
	v_mbcnt_hi_u32_b32 v2, s13, v2
	v_cmp_eq_u32_e32 vcc, 0, v2
	s_waitcnt vmcnt(0)
	s_and_saveexec_b64 s[6:7], vcc
	s_cbranch_execz .LBB0_854
	s_bcnt1_i32_b64 s2, s[12:13]
	v_mov_b32_e32 v2, s2
	s_nop 0
	s_nop 0

; __device__ __forceinline__ unsigned xb_add(unsigned* p, unsigned v) { return __hip_atomic_fetch_add(p, v, __ATOMIC_RELAXED, __HIP_MEMORY_SCOPE_AGENT); }
; __device__ __forceinline__ void xcd_barrier(const XcdBarrier& b, const bool leader) {
;     ...
;             xb_add(&bar[XB_XGEN(b.x)], 1u);
;             asm volatile("s_waitcnt vmcnt(0)" ::: "memory");
.LBB0_1061:
	s_or_b64 exec, exec, s[6:7]
	s_mov_b64 s[12:13], exec
	v_mbcnt_lo_u32_b32 v2, s12, 0
	v_mbcnt_hi_u32_b32 v2, s13, v2
	v_cmp_eq_u32_e32 vcc, 0, v2
	s_waitcnt vmcnt(0)
	s_and_saveexec_b64 s[6:7], vcc
	s_cbranch_execz .LBB0_345
	s_bcnt1_i32_b64 s2, s[12:13]
	v_mov_b32_e32 v2, s2
	s_nop 0
	s_nop 0
	s_branch .LBB0_345

; __device__ __forceinline__ unsigned xb_add(unsigned* p, unsigned v) { return __hip_atomic_fetch_add(p, v, __ATOMIC_RELAXED, __HIP_MEMORY_SCOPE_AGENT); }
; __device__ __forceinline__ void xcd_barrier(const XcdBarrier& b, const bool leader) {
;     ...
;             xb_add(&bar[XB_XGEN(b.x)], 1u);
;             asm volatile("s_waitcnt vmcnt(0)" ::: "memory");
.LBB0_1146:
	s_or_b64 exec, exec, s[10:11]
	s_mov_b64 s[10:11], exec
	v_mbcnt_lo_u32_b32 v0, s10, 0
	v_mbcnt_hi_u32_b32 v0, s11, v0
	v_cmp_eq_u32_e32 vcc, 0, v0
	s_waitcnt vmcnt(0)
	s_and_saveexec_b64 s[12:13], vcc
	s_cbranch_execz .LBB0_1148
	s_bcnt1_i32_b64 s0, s[10:11]
	v_mov_b32_e32 v0, 0x2000
	v_mov_b32_e32 v1, s0
	s_nop 0
	s_nop 0
.LBB0_1148:
	s_or_b64 exec, exec, s[12:13]
	s_nop 0

; __device__ __forceinline__ unsigned xb_add(unsigned* p, unsigned v) { return __hip_atomic_fetch_add(p, v, __ATOMIC_RELAXED, __HIP_MEMORY_SCOPE_AGENT); }
; __device__ __forceinline__ void xcd_barrier(const XcdBarrier& b, const bool leader) {
;     ...
;             xb_add(&bar[XB_XGEN(b.x)], 1u);
;             asm volatile("s_waitcnt vmcnt(0)" ::: "memory");
.LBB0_1229:
	s_or_b64 exec, exec, s[4:5]
	s_mov_b64 s[4:5], exec
	v_mbcnt_lo_u32_b32 v0, s4, 0
	v_mbcnt_hi_u32_b32 v0, s5, v0
	v_cmp_eq_u32_e32 vcc, 0, v0
	s_waitcnt vmcnt(0)
	s_and_saveexec_b64 s[8:9], vcc
	s_cbranch_execz .LBB0_1231
	s_bcnt1_i32_b64 s0, s[4:5]
	v_mov_b32_e32 v0, 0x2000
	v_mov_b32_e32 v1, s0
	s_nop 0
	s_nop 0
.LBB0_1231:
	s_or_b64 exec, exec, s[8:9]
	s_nop 0
